# layer-1 table conversion spread over P6/P8/P15/P17 GEMM tails on fully idle CUs
# baseline (speedup 1.0000x reference)
.Ltc_p6:
	s_mov_b64 exec, -1
	v_readlane_b32 s84, v245, 0
	s_nop 3
	s_and_b32 s97, s84, 0xff
	s_cmp_lt_u32 s97, 40
	s_cbranch_scc1 .Ltc_p6_end
	v_and_b32_e32 v255, 63, v0
	v_lshlrev_b32_e32 v254, 6, v255
	v_lshlrev_b32_e32 v255, 3, v255
	v_mov_b32_e32 v251, 0
	v_readfirstlane_b32 s96, v0
	v_readlane_b32 s98, v244, 22
	v_readlane_b32 s99, v244, 23
	v_readlane_b32 s100, v244, 24
	v_readlane_b32 s101, v244, 25
	s_nop 3
	s_and_b32 s96, s96, 0x3ff
	s_lshr_b32 s96, s96, 6
	s_sub_u32 s97, s97, 40
	s_lshr_b32 s84, s84, 8
	s_mul_i32 s84, s84, 216
	s_add_u32 s84, s84, s97
	s_lshl_b32 s84, s84, 2
	s_add_u32 s84, s84, s96
	s_add_u32 s84, s84, 0x8000
	s_mov_b32 s85, 1728
	s_mov_b32 s91, 0x40c00000
	s_cmp_ge_u32 s84, 0x9770
	s_cbranch_scc1 .Ltc_p6_end
	s_mov_b32 s90, s84
.Ltc_p6_last:
	s_add_u32 s87, s90, s85
	s_cmp_ge_u32 s87, 0x9770
	s_cbranch_scc1 .Ltc_p6_lastd
	s_mov_b32 s90, s87
	s_branch .Ltc_p6_last

.Ltc_p6_loop:
	s_cmp_ge_u32 s84, 0x9770
	s_cbranch_scc1 .Ltc_p6_done
	s_waitcnt vmcnt(12)
	v_max_f32_e64 v240, |v176|, |v177|
	v_max3_f32 v240, |v178|, |v179|, v240
	v_max3_f32 v240, |v180|, |v181|, v240
	v_max3_f32 v240, |v182|, |v183|, v240
	v_max3_f32 v240, |v184|, |v185|, v240
	v_max3_f32 v240, |v186|, |v187|, v240
	v_max3_f32 v240, |v188|, |v189|, v240
	v_max3_f32 v240, |v190|, |v191|, v240
	s_nop 1
	v_mov_b32_dpp v241, v240 quad_perm:[1,0,3,2] row_mask:0xf bank_mask:0xf bound_ctrl:1
	v_max_f32_e32 v241, v241, v241
	v_max_f32_e32 v240, v240, v241
	s_nop 1
	v_mov_b32_dpp v241, v240 quad_perm:[2,3,0,1] row_mask:0xf bank_mask:0xf bound_ctrl:1
	v_max_f32_e32 v241, v241, v241
	v_max_f32_e32 v240, v240, v241
	s_nop 1
	v_mov_b32_dpp v241, v240 row_half_mirror row_mask:0xf bank_mask:0xf bound_ctrl:1
	v_max_f32_e32 v241, v241, v241
	v_max_f32_e32 v240, v240, v241
	s_nop 1
	v_mov_b32_dpp v241, v240 row_mirror row_mask:0xf bank_mask:0xf bound_ctrl:1
	v_max_f32_e32 v241, v241, v241
	v_max_f32_e32 v240, v240, v241
	s_nop 0
	v_readlane_b32 s96, v240, 32
	v_readlane_b32 s97, v240, 48
	v_readlane_b32 s92, v240, 0
	v_readlane_b32 s93, v240, 16
	s_nop 1
	v_max_f32_e64 v240, s97, s97
	v_max_f32_e64 v241, s96, s96
	v_mov_b32_e32 v248, s93
	v_max_f32_e32 v240, v241, v240
	v_max3_f32 v240, s92, v248, v240
	v_div_scale_f32 v243, s[92:93], v240, v240, s91
	v_rcp_f32_e32 v246, v243
	v_div_scale_f32 v247, vcc, s91, v240, s91
	v_fma_f32 v248, -v243, v246, 1.0
	v_fmac_f32_e32 v246, v248, v246
	v_mul_f32_e32 v249, v247, v246
	v_fma_f32 v248, -v243, v249, v247
	v_fmac_f32_e32 v249, v248, v246
	v_fma_f32 v248, -v243, v249, v247
	v_div_fmas_f32 v242, v248, v246, v249
	v_div_fixup_f32 v242, v242, v240, s91
	v_cmp_lt_f32_e32 vcc, 0, v240
	v_mov_b32_e32 v252, 0
	v_mov_b32_e32 v253, 0
	v_cndmask_b32_e32 v242, 0, v242, vcc
	v_mul_f32_e32 v250, 0x3e2aaaab, v240
	v_mul_f32_e32 v176, v176, v242
	v_mul_f32_e32 v177, v177, v242
	v_mul_f32_e32 v178, v178, v242
	v_mul_f32_e32 v179, v179, v242
	v_mul_f32_e32 v180, v180, v242
	v_mul_f32_e32 v181, v181, v242
	v_mul_f32_e32 v182, v182, v242
	v_mul_f32_e32 v183, v183, v242
	v_mul_f32_e32 v184, v184, v242
	v_mul_f32_e32 v185, v185, v242
	v_mul_f32_e32 v186, v186, v242
	v_mul_f32_e32 v187, v187, v242
	v_mul_f32_e32 v188, v188, v242
	v_mul_f32_e32 v189, v189, v242
	v_mul_f32_e32 v190, v190, v242
	v_mul_f32_e32 v191, v191, v242
	v_cvt_scalef32_pk_fp4_f32 v252, v176, v177, 1.0
	v_cvt_scalef32_pk_fp4_f32 v253, v184, v185, 1.0
	v_cvt_scalef32_pk_fp4_f32 v252, v178, v179, 1.0 op_sel:[0,0,1,0]
	v_cvt_scalef32_pk_fp4_f32 v253, v186, v187, 1.0 op_sel:[0,0,1,0]
	v_cvt_scalef32_pk_fp4_f32 v252, v180, v181, 1.0 op_sel:[0,0,0,1]
	v_cvt_scalef32_pk_fp4_f32 v253, v188, v189, 1.0 op_sel:[0,0,0,1]
	v_cvt_scalef32_pk_fp4_f32 v252, v182, v183, 1.0 op_sel:[0,0,1,1]
	v_cvt_scalef32_pk_fp4_f32 v253, v190, v191, 1.0 op_sel:[0,0,1,1]
	v_readlane_b32 s88, v244, 28
	v_readlane_b32 s89, v244, 29
	s_lshl_b32 s96, s84, 9
	s_nop 1
	s_add_u32 s88, s88, 0x4280000
	s_addc_u32 s89, s89, 0
	s_add_u32 s88, s88, s96
	s_addc_u32 s89, s89, 0
	s_nop 0
	global_store_dwordx2 v255, v[252:253], s[88:89]
	v_readlane_b32 s88, v244, 28
	v_readlane_b32 s89, v244, 29
	s_lshl_b32 s96, s84, 2
	s_nop 1
	s_add_u32 s88, s88, 0xa310800
	s_addc_u32 s89, s89, 0
	s_add_u32 s88, s88, s96
	s_addc_u32 s89, s89, 0
	s_mov_b64 exec, 1
	global_store_dword v251, v250, s[88:89]
	s_mov_b64 exec, -1
	s_add_u32 s86, s86, s85
	s_min_u32 s87, s86, s90
	s_and_b32 s96, s87, 0x4000
	s_cmp_eq_u32 s96, 0
	s_cselect_b32 s94, s98, s100
	s_cselect_b32 s95, s99, s101
	s_and_b32 s96, s87, 0x3fff
	s_lshl_b32 s96, s96, 12
	s_add_u32 s94, s94, s96
	s_addc_u32 s95, s95, 0
	s_lshr_b32 s96, s87, 15
	s_lshl_b32 s96, s96, 26
	s_add_u32 s94, s94, s96
	s_addc_u32 s95, s95, 0
	global_load_dwordx4 v[224:227], v254, s[94:95] nt
	global_load_dwordx4 v[228:231], v254, s[94:95] offset:16 nt
	global_load_dwordx4 v[232:235], v254, s[94:95] offset:32 nt
	global_load_dwordx4 v[236:239], v254, s[94:95] offset:48 nt
	s_add_u32 s84, s84, s85
	s_cmp_ge_u32 s84, 0x9770
	s_cbranch_scc1 .Ltc_p6_done
	s_waitcnt vmcnt(12)
	v_max_f32_e64 v240, |v192|, |v193|
	v_max3_f32 v240, |v194|, |v195|, v240
	v_max3_f32 v240, |v196|, |v197|, v240
	v_max3_f32 v240, |v198|, |v199|, v240
	v_max3_f32 v240, |v200|, |v201|, v240
	v_max3_f32 v240, |v202|, |v203|, v240
	v_max3_f32 v240, |v204|, |v205|, v240
	v_max3_f32 v240, |v206|, |v207|, v240
	s_nop 1
	v_mov_b32_dpp v241, v240 quad_perm:[1,0,3,2] row_mask:0xf bank_mask:0xf bound_ctrl:1
	v_max_f32_e32 v241, v241, v241
	v_max_f32_e32 v240, v240, v241
	s_nop 1
	v_mov_b32_dpp v241, v240 quad_perm:[2,3,0,1] row_mask:0xf bank_mask:0xf bound_ctrl:1
	v_max_f32_e32 v241, v241, v241
	v_max_f32_e32 v240, v240, v241
	s_nop 1
	v_mov_b32_dpp v241, v240 row_half_mirror row_mask:0xf bank_mask:0xf bound_ctrl:1
	v_max_f32_e32 v241, v241, v241
	v_max_f32_e32 v240, v240, v241
	s_nop 1
	v_mov_b32_dpp v241, v240 row_mirror row_mask:0xf bank_mask:0xf bound_ctrl:1
	v_max_f32_e32 v241, v241, v241
	v_max_f32_e32 v240, v240, v241
	s_nop 0
	v_readlane_b32 s96, v240, 32
	v_readlane_b32 s97, v240, 48
	v_readlane_b32 s92, v240, 0
	v_readlane_b32 s93, v240, 16
	s_nop 1
	v_max_f32_e64 v240, s97, s97
	v_max_f32_e64 v241, s96, s96
	v_mov_b32_e32 v248, s93
	v_max_f32_e32 v240, v241, v240
	v_max3_f32 v240, s92, v248, v240
	v_div_scale_f32 v243, s[92:93], v240, v240, s91
	v_rcp_f32_e32 v246, v243
	v_div_scale_f32 v247, vcc, s91, v240, s91
	v_fma_f32 v248, -v243, v246, 1.0
	v_fmac_f32_e32 v246, v248, v246
	v_mul_f32_e32 v249, v247, v246
	v_fma_f32 v248, -v243, v249, v247
	v_fmac_f32_e32 v249, v248, v246
	v_fma_f32 v248, -v243, v249, v247
	v_div_fmas_f32 v242, v248, v246, v249
	v_div_fixup_f32 v242, v242, v240, s91
	v_cmp_lt_f32_e32 vcc, 0, v240
	v_mov_b32_e32 v252, 0
	v_mov_b32_e32 v253, 0
	v_cndmask_b32_e32 v242, 0, v242, vcc
	v_mul_f32_e32 v250, 0x3e2aaaab, v240
	v_mul_f32_e32 v192, v192, v242
	v_mul_f32_e32 v193, v193, v242
	v_mul_f32_e32 v194, v194, v242
	v_mul_f32_e32 v195, v195, v242
	v_mul_f32_e32 v196, v196, v242
	v_mul_f32_e32 v197, v197, v242
	v_mul_f32_e32 v198, v198, v242
	v_mul_f32_e32 v199, v199, v242
	v_mul_f32_e32 v200, v200, v242
	v_mul_f32_e32 v201, v201, v242
	v_mul_f32_e32 v202, v202, v242
	v_mul_f32_e32 v203, v203, v242
	v_mul_f32_e32 v204, v204, v242
	v_mul_f32_e32 v205, v205, v242
	v_mul_f32_e32 v206, v206, v242
	v_mul_f32_e32 v207, v207, v242
	v_cvt_scalef32_pk_fp4_f32 v252, v192, v193, 1.0
	v_cvt_scalef32_pk_fp4_f32 v253, v200, v201, 1.0
	v_cvt_scalef32_pk_fp4_f32 v252, v194, v195, 1.0 op_sel:[0,0,1,0]
	v_cvt_scalef32_pk_fp4_f32 v253, v202, v203, 1.0 op_sel:[0,0,1,0]
	v_cvt_scalef32_pk_fp4_f32 v252, v196, v197, 1.0 op_sel:[0,0,0,1]
	v_cvt_scalef32_pk_fp4_f32 v253, v204, v205, 1.0 op_sel:[0,0,0,1]
	v_cvt_scalef32_pk_fp4_f32 v252, v198, v199, 1.0 op_sel:[0,0,1,1]
	v_cvt_scalef32_pk_fp4_f32 v253, v206, v207, 1.0 op_sel:[0,0,1,1]
	v_readlane_b32 s88, v244, 28
	v_readlane_b32 s89, v244, 29
	s_lshl_b32 s96, s84, 9
	s_nop 1
	s_add_u32 s88, s88, 0x4280000
	s_addc_u32 s89, s89, 0
	s_add_u32 s88, s88, s96
	s_addc_u32 s89, s89, 0
	s_nop 0
	global_store_dwordx2 v255, v[252:253], s[88:89]
	v_readlane_b32 s88, v244, 28
	v_readlane_b32 s89, v244, 29
	s_lshl_b32 s96, s84, 2
	s_nop 1
	s_add_u32 s88, s88, 0xa310800
	s_addc_u32 s89, s89, 0
	s_add_u32 s88, s88, s96
	s_addc_u32 s89, s89, 0
	s_mov_b64 exec, 1
	global_store_dword v251, v250, s[88:89]
	s_mov_b64 exec, -1
	s_add_u32 s86, s86, s85
	s_min_u32 s87, s86, s90
	s_and_b32 s96, s87, 0x4000
	s_cmp_eq_u32 s96, 0
	s_cselect_b32 s94, s98, s100
	s_cselect_b32 s95, s99, s101
	s_and_b32 s96, s87, 0x3fff
	s_lshl_b32 s96, s96, 12
	s_add_u32 s94, s94, s96
	s_addc_u32 s95, s95, 0
	s_lshr_b32 s96, s87, 15
	s_lshl_b32 s96, s96, 26
	s_add_u32 s94, s94, s96
	s_addc_u32 s95, s95, 0
	global_load_dwordx4 v[176:179], v254, s[94:95] nt
	global_load_dwordx4 v[180:183], v254, s[94:95] offset:16 nt
	global_load_dwordx4 v[184:187], v254, s[94:95] offset:32 nt
	global_load_dwordx4 v[188:191], v254, s[94:95] offset:48 nt
	s_add_u32 s84, s84, s85
	s_cmp_ge_u32 s84, 0x9770
	s_cbranch_scc1 .Ltc_p6_done
	s_waitcnt vmcnt(12)
	v_max_f32_e64 v240, |v208|, |v209|
	v_max3_f32 v240, |v210|, |v211|, v240
	v_max3_f32 v240, |v212|, |v213|, v240
	v_max3_f32 v240, |v214|, |v215|, v240
	v_max3_f32 v240, |v216|, |v217|, v240
	v_max3_f32 v240, |v218|, |v219|, v240
	v_max3_f32 v240, |v220|, |v221|, v240
	v_max3_f32 v240, |v222|, |v223|, v240
	s_nop 1
	v_mov_b32_dpp v241, v240 quad_perm:[1,0,3,2] row_mask:0xf bank_mask:0xf bound_ctrl:1
	v_max_f32_e32 v241, v241, v241
	v_max_f32_e32 v240, v240, v241
	s_nop 1
	v_mov_b32_dpp v241, v240 quad_perm:[2,3,0,1] row_mask:0xf bank_mask:0xf bound_ctrl:1
	v_max_f32_e32 v241, v241, v241
	v_max_f32_e32 v240, v240, v241
	s_nop 1
	v_mov_b32_dpp v241, v240 row_half_mirror row_mask:0xf bank_mask:0xf bound_ctrl:1
	v_max_f32_e32 v241, v241, v241
	v_max_f32_e32 v240, v240, v241
	s_nop 1
	v_mov_b32_dpp v241, v240 row_mirror row_mask:0xf bank_mask:0xf bound_ctrl:1
	v_max_f32_e32 v241, v241, v241
	v_max_f32_e32 v240, v240, v241
	s_nop 0
	v_readlane_b32 s96, v240, 32
	v_readlane_b32 s97, v240, 48
	v_readlane_b32 s92, v240, 0
	v_readlane_b32 s93, v240, 16
	s_nop 1
	v_max_f32_e64 v240, s97, s97
	v_max_f32_e64 v241, s96, s96
	v_mov_b32_e32 v248, s93
	v_max_f32_e32 v240, v241, v240
	v_max3_f32 v240, s92, v248, v240
	v_div_scale_f32 v243, s[92:93], v240, v240, s91
	v_rcp_f32_e32 v246, v243
	v_div_scale_f32 v247, vcc, s91, v240, s91
	v_fma_f32 v248, -v243, v246, 1.0
	v_fmac_f32_e32 v246, v248, v246
	v_mul_f32_e32 v249, v247, v246
	v_fma_f32 v248, -v243, v249, v247
	v_fmac_f32_e32 v249, v248, v246
	v_fma_f32 v248, -v243, v249, v247
	v_div_fmas_f32 v242, v248, v246, v249
	v_div_fixup_f32 v242, v242, v240, s91
	v_cmp_lt_f32_e32 vcc, 0, v240
	v_mov_b32_e32 v252, 0
	v_mov_b32_e32 v253, 0
	v_cndmask_b32_e32 v242, 0, v242, vcc
	v_mul_f32_e32 v250, 0x3e2aaaab, v240
	v_mul_f32_e32 v208, v208, v242
	v_mul_f32_e32 v209, v209, v242
	v_mul_f32_e32 v210, v210, v242
	v_mul_f32_e32 v211, v211, v242
	v_mul_f32_e32 v212, v212, v242
	v_mul_f32_e32 v213, v213, v242
	v_mul_f32_e32 v214, v214, v242
	v_mul_f32_e32 v215, v215, v242
	v_mul_f32_e32 v216, v216, v242
	v_mul_f32_e32 v217, v217, v242
	v_mul_f32_e32 v218, v218, v242
	v_mul_f32_e32 v219, v219, v242
	v_mul_f32_e32 v220, v220, v242
	v_mul_f32_e32 v221, v221, v242
	v_mul_f32_e32 v222, v222, v242
	v_mul_f32_e32 v223, v223, v242
	v_cvt_scalef32_pk_fp4_f32 v252, v208, v209, 1.0
	v_cvt_scalef32_pk_fp4_f32 v253, v216, v217, 1.0
	v_cvt_scalef32_pk_fp4_f32 v252, v210, v211, 1.0 op_sel:[0,0,1,0]
	v_cvt_scalef32_pk_fp4_f32 v253, v218, v219, 1.0 op_sel:[0,0,1,0]
	v_cvt_scalef32_pk_fp4_f32 v252, v212, v213, 1.0 op_sel:[0,0,0,1]
	v_cvt_scalef32_pk_fp4_f32 v253, v220, v221, 1.0 op_sel:[0,0,0,1]
	v_cvt_scalef32_pk_fp4_f32 v252, v214, v215, 1.0 op_sel:[0,0,1,1]
	v_cvt_scalef32_pk_fp4_f32 v253, v222, v223, 1.0 op_sel:[0,0,1,1]
	v_readlane_b32 s88, v244, 28
	v_readlane_b32 s89, v244, 29
	s_lshl_b32 s96, s84, 9
	s_nop 1
	s_add_u32 s88, s88, 0x4280000
	s_addc_u32 s89, s89, 0
	s_add_u32 s88, s88, s96
	s_addc_u32 s89, s89, 0
	s_nop 0
	global_store_dwordx2 v255, v[252:253], s[88:89]
	v_readlane_b32 s88, v244, 28
	v_readlane_b32 s89, v244, 29
	s_lshl_b32 s96, s84, 2
	s_nop 1
	s_add_u32 s88, s88, 0xa310800
	s_addc_u32 s89, s89, 0
	s_add_u32 s88, s88, s96
	s_addc_u32 s89, s89, 0
	s_mov_b64 exec, 1
	global_store_dword v251, v250, s[88:89]
	s_mov_b64 exec, -1
	s_add_u32 s86, s86, s85
	s_min_u32 s87, s86, s90
	s_and_b32 s96, s87, 0x4000
	s_cmp_eq_u32 s96, 0
	s_cselect_b32 s94, s98, s100
	s_cselect_b32 s95, s99, s101
	s_and_b32 s96, s87, 0x3fff
	s_lshl_b32 s96, s96, 12
	s_add_u32 s94, s94, s96
	s_addc_u32 s95, s95, 0
	s_lshr_b32 s96, s87, 15
	s_lshl_b32 s96, s96, 26
	s_add_u32 s94, s94, s96
	s_addc_u32 s95, s95, 0
	global_load_dwordx4 v[192:195], v254, s[94:95] nt
	global_load_dwordx4 v[196:199], v254, s[94:95] offset:16 nt
	global_load_dwordx4 v[200:203], v254, s[94:95] offset:32 nt
	global_load_dwordx4 v[204:207], v254, s[94:95] offset:48 nt
	s_add_u32 s84, s84, s85
	s_cmp_ge_u32 s84, 0x9770
	s_cbranch_scc1 .Ltc_p6_done
	s_waitcnt vmcnt(12)
	v_max_f32_e64 v240, |v224|, |v225|
	v_max3_f32 v240, |v226|, |v227|, v240
	v_max3_f32 v240, |v228|, |v229|, v240
	v_max3_f32 v240, |v230|, |v231|, v240
	v_max3_f32 v240, |v232|, |v233|, v240
	v_max3_f32 v240, |v234|, |v235|, v240
	v_max3_f32 v240, |v236|, |v237|, v240
	v_max3_f32 v240, |v238|, |v239|, v240
	s_nop 1
	v_mov_b32_dpp v241, v240 quad_perm:[1,0,3,2] row_mask:0xf bank_mask:0xf bound_ctrl:1
	v_max_f32_e32 v241, v241, v241
	v_max_f32_e32 v240, v240, v241
	s_nop 1
	v_mov_b32_dpp v241, v240 quad_perm:[2,3,0,1] row_mask:0xf bank_mask:0xf bound_ctrl:1
	v_max_f32_e32 v241, v241, v241
	v_max_f32_e32 v240, v240, v241
	s_nop 1
	v_mov_b32_dpp v241, v240 row_half_mirror row_mask:0xf bank_mask:0xf bound_ctrl:1
	v_max_f32_e32 v241, v241, v241
	v_max_f32_e32 v240, v240, v241
	s_nop 1
	v_mov_b32_dpp v241, v240 row_mirror row_mask:0xf bank_mask:0xf bound_ctrl:1
	v_max_f32_e32 v241, v241, v241
	v_max_f32_e32 v240, v240, v241
	s_nop 0
	v_readlane_b32 s96, v240, 32
	v_readlane_b32 s97, v240, 48
	v_readlane_b32 s92, v240, 0
	v_readlane_b32 s93, v240, 16
	s_nop 1
	v_max_f32_e64 v240, s97, s97
	v_max_f32_e64 v241, s96, s96
	v_mov_b32_e32 v248, s93
	v_max_f32_e32 v240, v241, v240
	v_max3_f32 v240, s92, v248, v240
	v_div_scale_f32 v243, s[92:93], v240, v240, s91
	v_rcp_f32_e32 v246, v243
	v_div_scale_f32 v247, vcc, s91, v240, s91
	v_fma_f32 v248, -v243, v246, 1.0
	v_fmac_f32_e32 v246, v248, v246
	v_mul_f32_e32 v249, v247, v246
	v_fma_f32 v248, -v243, v249, v247
	v_fmac_f32_e32 v249, v248, v246
	v_fma_f32 v248, -v243, v249, v247
	v_div_fmas_f32 v242, v248, v246, v249
	v_div_fixup_f32 v242, v242, v240, s91
	v_cmp_lt_f32_e32 vcc, 0, v240
	v_mov_b32_e32 v252, 0
	v_mov_b32_e32 v253, 0
	v_cndmask_b32_e32 v242, 0, v242, vcc
	v_mul_f32_e32 v250, 0x3e2aaaab, v240
	v_mul_f32_e32 v224, v224, v242
	v_mul_f32_e32 v225, v225, v242
	v_mul_f32_e32 v226, v226, v242
	v_mul_f32_e32 v227, v227, v242
	v_mul_f32_e32 v228, v228, v242
	v_mul_f32_e32 v229, v229, v242
	v_mul_f32_e32 v230, v230, v242
	v_mul_f32_e32 v231, v231, v242
	v_mul_f32_e32 v232, v232, v242
	v_mul_f32_e32 v233, v233, v242
	v_mul_f32_e32 v234, v234, v242
	v_mul_f32_e32 v235, v235, v242
	v_mul_f32_e32 v236, v236, v242
	v_mul_f32_e32 v237, v237, v242
	v_mul_f32_e32 v238, v238, v242
	v_mul_f32_e32 v239, v239, v242
	v_cvt_scalef32_pk_fp4_f32 v252, v224, v225, 1.0
	v_cvt_scalef32_pk_fp4_f32 v253, v232, v233, 1.0
	v_cvt_scalef32_pk_fp4_f32 v252, v226, v227, 1.0 op_sel:[0,0,1,0]
	v_cvt_scalef32_pk_fp4_f32 v253, v234, v235, 1.0 op_sel:[0,0,1,0]
	v_cvt_scalef32_pk_fp4_f32 v252, v228, v229, 1.0 op_sel:[0,0,0,1]
	v_cvt_scalef32_pk_fp4_f32 v253, v236, v237, 1.0 op_sel:[0,0,0,1]
	v_cvt_scalef32_pk_fp4_f32 v252, v230, v231, 1.0 op_sel:[0,0,1,1]
	v_cvt_scalef32_pk_fp4_f32 v253, v238, v239, 1.0 op_sel:[0,0,1,1]
	v_readlane_b32 s88, v244, 28
	v_readlane_b32 s89, v244, 29
	s_lshl_b32 s96, s84, 9
	s_nop 1
	s_add_u32 s88, s88, 0x4280000
	s_addc_u32 s89, s89, 0
	s_add_u32 s88, s88, s96
	s_addc_u32 s89, s89, 0
	s_nop 0
	global_store_dwordx2 v255, v[252:253], s[88:89]
	v_readlane_b32 s88, v244, 28
	v_readlane_b32 s89, v244, 29
	s_lshl_b32 s96, s84, 2
	s_nop 1
	s_add_u32 s88, s88, 0xa310800
	s_addc_u32 s89, s89, 0
	s_add_u32 s88, s88, s96
	s_addc_u32 s89, s89, 0
	s_mov_b64 exec, 1
	global_store_dword v251, v250, s[88:89]
	s_mov_b64 exec, -1
	s_add_u32 s86, s86, s85
	s_min_u32 s87, s86, s90
	s_and_b32 s96, s87, 0x4000
	s_cmp_eq_u32 s96, 0
	s_cselect_b32 s94, s98, s100
	s_cselect_b32 s95, s99, s101
	s_and_b32 s96, s87, 0x3fff
	s_lshl_b32 s96, s96, 12
	s_add_u32 s94, s94, s96
	s_addc_u32 s95, s95, 0
	s_lshr_b32 s96, s87, 15
	s_lshl_b32 s96, s96, 26
	s_add_u32 s94, s94, s96
	s_addc_u32 s95, s95, 0
	global_load_dwordx4 v[208:211], v254, s[94:95] nt
	global_load_dwordx4 v[212:215], v254, s[94:95] offset:16 nt
	global_load_dwordx4 v[216:219], v254, s[94:95] offset:32 nt
	global_load_dwordx4 v[220:223], v254, s[94:95] offset:48 nt
	s_add_u32 s84, s84, s85
	s_branch .Ltc_p6_loop

.Ltc_p6_end:
.LBB0_1744:
	v_readlane_b32 s4, v245, 7
	v_readlane_b32 s5, v245, 8
	s_cmp_gt_i32 s4, 7
	s_cselect_b64 s[0:1], -1, 0
	s_cmp_lt_i32 s5, 8
	s_cselect_b64 s[2:3], -1, 0
	s_or_b64 s[2:3], s[0:1], s[2:3]
	s_and_b64 vcc, exec, s[2:3]
	v_readlane_b32 s6, v245, 9
	v_readlane_b32 s7, v245, 10
	s_cbranch_vccnz .LBB0_1814
	s_andn2_b64 vcc, exec, s[12:13]
	s_cbranch_vccnz .LBB0_1747
	v_and_b32_e32 v1, 0x3ff, v0
	s_cbranch_execz .LBB0_1748
	s_branch .LBB0_1810

.Ltc_p8:
	s_mov_b64 exec, -1
	v_readlane_b32 s84, v245, 0
	s_nop 3
	s_and_b32 s97, s84, 0xff
	s_cmp_lt_u32 s97, 80
	s_cbranch_scc1 .Ltc_p8_end
	v_and_b32_e32 v255, 63, v0
	v_lshlrev_b32_e32 v254, 6, v255
	v_lshlrev_b32_e32 v255, 3, v255
	v_mov_b32_e32 v251, 0
	v_readfirstlane_b32 s96, v0
	v_readlane_b32 s98, v244, 22
	v_readlane_b32 s99, v244, 23
	v_readlane_b32 s100, v244, 24
	v_readlane_b32 s101, v244, 25
	s_nop 3
	s_and_b32 s96, s96, 0x3ff
	s_lshr_b32 s96, s96, 6
	s_sub_u32 s97, s97, 80
	s_lshr_b32 s84, s84, 8
	s_mul_i32 s84, s84, 176
	s_add_u32 s84, s84, s97
	s_lshl_b32 s84, s84, 2
	s_add_u32 s84, s84, s96
	s_add_u32 s84, s84, 0x9770
	s_mov_b32 s85, 1408
	s_mov_b32 s91, 0x40c00000
	s_cmp_ge_u32 s84, 0xba98
	s_cbranch_scc1 .Ltc_p8_end
	s_mov_b32 s90, s84
.Ltc_p8_last:
	s_add_u32 s87, s90, s85
	s_cmp_ge_u32 s87, 0xba98
	s_cbranch_scc1 .Ltc_p8_lastd
	s_mov_b32 s90, s87
	s_branch .Ltc_p8_last

.Ltc_p8_loop:
	s_cmp_ge_u32 s84, 0xba98
	s_cbranch_scc1 .Ltc_p8_done
	s_waitcnt vmcnt(12)
	v_max_f32_e64 v240, |v176|, |v177|
	v_max3_f32 v240, |v178|, |v179|, v240
	v_max3_f32 v240, |v180|, |v181|, v240
	v_max3_f32 v240, |v182|, |v183|, v240
	v_max3_f32 v240, |v184|, |v185|, v240
	v_max3_f32 v240, |v186|, |v187|, v240
	v_max3_f32 v240, |v188|, |v189|, v240
	v_max3_f32 v240, |v190|, |v191|, v240
	s_nop 1
	v_mov_b32_dpp v241, v240 quad_perm:[1,0,3,2] row_mask:0xf bank_mask:0xf bound_ctrl:1
	v_max_f32_e32 v241, v241, v241
	v_max_f32_e32 v240, v240, v241
	s_nop 1
	v_mov_b32_dpp v241, v240 quad_perm:[2,3,0,1] row_mask:0xf bank_mask:0xf bound_ctrl:1
	v_max_f32_e32 v241, v241, v241
	v_max_f32_e32 v240, v240, v241
	s_nop 1
	v_mov_b32_dpp v241, v240 row_half_mirror row_mask:0xf bank_mask:0xf bound_ctrl:1
	v_max_f32_e32 v241, v241, v241
	v_max_f32_e32 v240, v240, v241
	s_nop 1
	v_mov_b32_dpp v241, v240 row_mirror row_mask:0xf bank_mask:0xf bound_ctrl:1
	v_max_f32_e32 v241, v241, v241
	v_max_f32_e32 v240, v240, v241
	s_nop 0
	v_readlane_b32 s96, v240, 32
	v_readlane_b32 s97, v240, 48
	v_readlane_b32 s92, v240, 0
	v_readlane_b32 s93, v240, 16
	s_nop 1
	v_max_f32_e64 v240, s97, s97
	v_max_f32_e64 v241, s96, s96
	v_mov_b32_e32 v248, s93
	v_max_f32_e32 v240, v241, v240
	v_max3_f32 v240, s92, v248, v240
	v_div_scale_f32 v243, s[92:93], v240, v240, s91
	v_rcp_f32_e32 v246, v243
	v_div_scale_f32 v247, vcc, s91, v240, s91
	v_fma_f32 v248, -v243, v246, 1.0
	v_fmac_f32_e32 v246, v248, v246
	v_mul_f32_e32 v249, v247, v246
	v_fma_f32 v248, -v243, v249, v247
	v_fmac_f32_e32 v249, v248, v246
	v_fma_f32 v248, -v243, v249, v247
	v_div_fmas_f32 v242, v248, v246, v249
	v_div_fixup_f32 v242, v242, v240, s91
	v_cmp_lt_f32_e32 vcc, 0, v240
	v_mov_b32_e32 v252, 0
	v_mov_b32_e32 v253, 0
	v_cndmask_b32_e32 v242, 0, v242, vcc
	v_mul_f32_e32 v250, 0x3e2aaaab, v240
	v_mul_f32_e32 v176, v176, v242
	v_mul_f32_e32 v177, v177, v242
	v_mul_f32_e32 v178, v178, v242
	v_mul_f32_e32 v179, v179, v242
	v_mul_f32_e32 v180, v180, v242
	v_mul_f32_e32 v181, v181, v242
	v_mul_f32_e32 v182, v182, v242
	v_mul_f32_e32 v183, v183, v242
	v_mul_f32_e32 v184, v184, v242
	v_mul_f32_e32 v185, v185, v242
	v_mul_f32_e32 v186, v186, v242
	v_mul_f32_e32 v187, v187, v242
	v_mul_f32_e32 v188, v188, v242
	v_mul_f32_e32 v189, v189, v242
	v_mul_f32_e32 v190, v190, v242
	v_mul_f32_e32 v191, v191, v242
	v_cvt_scalef32_pk_fp4_f32 v252, v176, v177, 1.0
	v_cvt_scalef32_pk_fp4_f32 v253, v184, v185, 1.0
	v_cvt_scalef32_pk_fp4_f32 v252, v178, v179, 1.0 op_sel:[0,0,1,0]
	v_cvt_scalef32_pk_fp4_f32 v253, v186, v187, 1.0 op_sel:[0,0,1,0]
	v_cvt_scalef32_pk_fp4_f32 v252, v180, v181, 1.0 op_sel:[0,0,0,1]
	v_cvt_scalef32_pk_fp4_f32 v253, v188, v189, 1.0 op_sel:[0,0,0,1]
	v_cvt_scalef32_pk_fp4_f32 v252, v182, v183, 1.0 op_sel:[0,0,1,1]
	v_cvt_scalef32_pk_fp4_f32 v253, v190, v191, 1.0 op_sel:[0,0,1,1]
	v_readlane_b32 s88, v244, 28
	v_readlane_b32 s89, v244, 29
	s_lshl_b32 s96, s84, 9
	s_nop 1
	s_add_u32 s88, s88, 0x4280000
	s_addc_u32 s89, s89, 0
	s_add_u32 s88, s88, s96
	s_addc_u32 s89, s89, 0
	s_nop 0
	global_store_dwordx2 v255, v[252:253], s[88:89]
	v_readlane_b32 s88, v244, 28
	v_readlane_b32 s89, v244, 29
	s_lshl_b32 s96, s84, 2
	s_nop 1
	s_add_u32 s88, s88, 0xa310800
	s_addc_u32 s89, s89, 0
	s_add_u32 s88, s88, s96
	s_addc_u32 s89, s89, 0
	s_mov_b64 exec, 1
	global_store_dword v251, v250, s[88:89]
	s_mov_b64 exec, -1
	s_add_u32 s86, s86, s85
	s_min_u32 s87, s86, s90
	s_and_b32 s96, s87, 0x4000
	s_cmp_eq_u32 s96, 0
	s_cselect_b32 s94, s98, s100
	s_cselect_b32 s95, s99, s101
	s_and_b32 s96, s87, 0x3fff
	s_lshl_b32 s96, s96, 12
	s_add_u32 s94, s94, s96
	s_addc_u32 s95, s95, 0
	s_lshr_b32 s96, s87, 15
	s_lshl_b32 s96, s96, 26
	s_add_u32 s94, s94, s96
	s_addc_u32 s95, s95, 0
	global_load_dwordx4 v[224:227], v254, s[94:95] nt
	global_load_dwordx4 v[228:231], v254, s[94:95] offset:16 nt
	global_load_dwordx4 v[232:235], v254, s[94:95] offset:32 nt
	global_load_dwordx4 v[236:239], v254, s[94:95] offset:48 nt
	s_add_u32 s84, s84, s85
	s_cmp_ge_u32 s84, 0xba98
	s_cbranch_scc1 .Ltc_p8_done
	s_waitcnt vmcnt(12)
	v_max_f32_e64 v240, |v192|, |v193|
	v_max3_f32 v240, |v194|, |v195|, v240
	v_max3_f32 v240, |v196|, |v197|, v240
	v_max3_f32 v240, |v198|, |v199|, v240
	v_max3_f32 v240, |v200|, |v201|, v240
	v_max3_f32 v240, |v202|, |v203|, v240
	v_max3_f32 v240, |v204|, |v205|, v240
	v_max3_f32 v240, |v206|, |v207|, v240
	s_nop 1
	v_mov_b32_dpp v241, v240 quad_perm:[1,0,3,2] row_mask:0xf bank_mask:0xf bound_ctrl:1
	v_max_f32_e32 v241, v241, v241
	v_max_f32_e32 v240, v240, v241
	s_nop 1
	v_mov_b32_dpp v241, v240 quad_perm:[2,3,0,1] row_mask:0xf bank_mask:0xf bound_ctrl:1
	v_max_f32_e32 v241, v241, v241
	v_max_f32_e32 v240, v240, v241
	s_nop 1
	v_mov_b32_dpp v241, v240 row_half_mirror row_mask:0xf bank_mask:0xf bound_ctrl:1
	v_max_f32_e32 v241, v241, v241
	v_max_f32_e32 v240, v240, v241
	s_nop 1
	v_mov_b32_dpp v241, v240 row_mirror row_mask:0xf bank_mask:0xf bound_ctrl:1
	v_max_f32_e32 v241, v241, v241
	v_max_f32_e32 v240, v240, v241
	s_nop 0
	v_readlane_b32 s96, v240, 32
	v_readlane_b32 s97, v240, 48
	v_readlane_b32 s92, v240, 0
	v_readlane_b32 s93, v240, 16
	s_nop 1
	v_max_f32_e64 v240, s97, s97
	v_max_f32_e64 v241, s96, s96
	v_mov_b32_e32 v248, s93
	v_max_f32_e32 v240, v241, v240
	v_max3_f32 v240, s92, v248, v240
	v_div_scale_f32 v243, s[92:93], v240, v240, s91
	v_rcp_f32_e32 v246, v243
	v_div_scale_f32 v247, vcc, s91, v240, s91
	v_fma_f32 v248, -v243, v246, 1.0
	v_fmac_f32_e32 v246, v248, v246
	v_mul_f32_e32 v249, v247, v246
	v_fma_f32 v248, -v243, v249, v247
	v_fmac_f32_e32 v249, v248, v246
	v_fma_f32 v248, -v243, v249, v247
	v_div_fmas_f32 v242, v248, v246, v249
	v_div_fixup_f32 v242, v242, v240, s91
	v_cmp_lt_f32_e32 vcc, 0, v240
	v_mov_b32_e32 v252, 0
	v_mov_b32_e32 v253, 0
	v_cndmask_b32_e32 v242, 0, v242, vcc
	v_mul_f32_e32 v250, 0x3e2aaaab, v240
	v_mul_f32_e32 v192, v192, v242
	v_mul_f32_e32 v193, v193, v242
	v_mul_f32_e32 v194, v194, v242
	v_mul_f32_e32 v195, v195, v242
	v_mul_f32_e32 v196, v196, v242
	v_mul_f32_e32 v197, v197, v242
	v_mul_f32_e32 v198, v198, v242
	v_mul_f32_e32 v199, v199, v242
	v_mul_f32_e32 v200, v200, v242
	v_mul_f32_e32 v201, v201, v242
	v_mul_f32_e32 v202, v202, v242
	v_mul_f32_e32 v203, v203, v242
	v_mul_f32_e32 v204, v204, v242
	v_mul_f32_e32 v205, v205, v242
	v_mul_f32_e32 v206, v206, v242
	v_mul_f32_e32 v207, v207, v242
	v_cvt_scalef32_pk_fp4_f32 v252, v192, v193, 1.0
	v_cvt_scalef32_pk_fp4_f32 v253, v200, v201, 1.0
	v_cvt_scalef32_pk_fp4_f32 v252, v194, v195, 1.0 op_sel:[0,0,1,0]
	v_cvt_scalef32_pk_fp4_f32 v253, v202, v203, 1.0 op_sel:[0,0,1,0]
	v_cvt_scalef32_pk_fp4_f32 v252, v196, v197, 1.0 op_sel:[0,0,0,1]
	v_cvt_scalef32_pk_fp4_f32 v253, v204, v205, 1.0 op_sel:[0,0,0,1]
	v_cvt_scalef32_pk_fp4_f32 v252, v198, v199, 1.0 op_sel:[0,0,1,1]
	v_cvt_scalef32_pk_fp4_f32 v253, v206, v207, 1.0 op_sel:[0,0,1,1]
	v_readlane_b32 s88, v244, 28
	v_readlane_b32 s89, v244, 29
	s_lshl_b32 s96, s84, 9
	s_nop 1
	s_add_u32 s88, s88, 0x4280000
	s_addc_u32 s89, s89, 0
	s_add_u32 s88, s88, s96
	s_addc_u32 s89, s89, 0
	s_nop 0
	global_store_dwordx2 v255, v[252:253], s[88:89]
	v_readlane_b32 s88, v244, 28
	v_readlane_b32 s89, v244, 29
	s_lshl_b32 s96, s84, 2
	s_nop 1
	s_add_u32 s88, s88, 0xa310800
	s_addc_u32 s89, s89, 0
	s_add_u32 s88, s88, s96
	s_addc_u32 s89, s89, 0
	s_mov_b64 exec, 1
	global_store_dword v251, v250, s[88:89]
	s_mov_b64 exec, -1
	s_add_u32 s86, s86, s85
	s_min_u32 s87, s86, s90
	s_and_b32 s96, s87, 0x4000
	s_cmp_eq_u32 s96, 0
	s_cselect_b32 s94, s98, s100
	s_cselect_b32 s95, s99, s101
	s_and_b32 s96, s87, 0x3fff
	s_lshl_b32 s96, s96, 12
	s_add_u32 s94, s94, s96
	s_addc_u32 s95, s95, 0
	s_lshr_b32 s96, s87, 15
	s_lshl_b32 s96, s96, 26
	s_add_u32 s94, s94, s96
	s_addc_u32 s95, s95, 0
	global_load_dwordx4 v[176:179], v254, s[94:95] nt
	global_load_dwordx4 v[180:183], v254, s[94:95] offset:16 nt
	global_load_dwordx4 v[184:187], v254, s[94:95] offset:32 nt
	global_load_dwordx4 v[188:191], v254, s[94:95] offset:48 nt
	s_add_u32 s84, s84, s85
	s_cmp_ge_u32 s84, 0xba98
	s_cbranch_scc1 .Ltc_p8_done
	s_waitcnt vmcnt(12)
	v_max_f32_e64 v240, |v208|, |v209|
	v_max3_f32 v240, |v210|, |v211|, v240
	v_max3_f32 v240, |v212|, |v213|, v240
	v_max3_f32 v240, |v214|, |v215|, v240
	v_max3_f32 v240, |v216|, |v217|, v240
	v_max3_f32 v240, |v218|, |v219|, v240
	v_max3_f32 v240, |v220|, |v221|, v240
	v_max3_f32 v240, |v222|, |v223|, v240
	s_nop 1
	v_mov_b32_dpp v241, v240 quad_perm:[1,0,3,2] row_mask:0xf bank_mask:0xf bound_ctrl:1
	v_max_f32_e32 v241, v241, v241
	v_max_f32_e32 v240, v240, v241
	s_nop 1
	v_mov_b32_dpp v241, v240 quad_perm:[2,3,0,1] row_mask:0xf bank_mask:0xf bound_ctrl:1
	v_max_f32_e32 v241, v241, v241
	v_max_f32_e32 v240, v240, v241
	s_nop 1
	v_mov_b32_dpp v241, v240 row_half_mirror row_mask:0xf bank_mask:0xf bound_ctrl:1
	v_max_f32_e32 v241, v241, v241
	v_max_f32_e32 v240, v240, v241
	s_nop 1
	v_mov_b32_dpp v241, v240 row_mirror row_mask:0xf bank_mask:0xf bound_ctrl:1
	v_max_f32_e32 v241, v241, v241
	v_max_f32_e32 v240, v240, v241
	s_nop 0
	v_readlane_b32 s96, v240, 32
	v_readlane_b32 s97, v240, 48
	v_readlane_b32 s92, v240, 0
	v_readlane_b32 s93, v240, 16
	s_nop 1
	v_max_f32_e64 v240, s97, s97
	v_max_f32_e64 v241, s96, s96
	v_mov_b32_e32 v248, s93
	v_max_f32_e32 v240, v241, v240
	v_max3_f32 v240, s92, v248, v240
	v_div_scale_f32 v243, s[92:93], v240, v240, s91
	v_rcp_f32_e32 v246, v243
	v_div_scale_f32 v247, vcc, s91, v240, s91
	v_fma_f32 v248, -v243, v246, 1.0
	v_fmac_f32_e32 v246, v248, v246
	v_mul_f32_e32 v249, v247, v246
	v_fma_f32 v248, -v243, v249, v247
	v_fmac_f32_e32 v249, v248, v246
	v_fma_f32 v248, -v243, v249, v247
	v_div_fmas_f32 v242, v248, v246, v249
	v_div_fixup_f32 v242, v242, v240, s91
	v_cmp_lt_f32_e32 vcc, 0, v240
	v_mov_b32_e32 v252, 0
	v_mov_b32_e32 v253, 0
	v_cndmask_b32_e32 v242, 0, v242, vcc
	v_mul_f32_e32 v250, 0x3e2aaaab, v240
	v_mul_f32_e32 v208, v208, v242
	v_mul_f32_e32 v209, v209, v242
	v_mul_f32_e32 v210, v210, v242
	v_mul_f32_e32 v211, v211, v242
	v_mul_f32_e32 v212, v212, v242
	v_mul_f32_e32 v213, v213, v242
	v_mul_f32_e32 v214, v214, v242
	v_mul_f32_e32 v215, v215, v242
	v_mul_f32_e32 v216, v216, v242
	v_mul_f32_e32 v217, v217, v242
	v_mul_f32_e32 v218, v218, v242
	v_mul_f32_e32 v219, v219, v242
	v_mul_f32_e32 v220, v220, v242
	v_mul_f32_e32 v221, v221, v242
	v_mul_f32_e32 v222, v222, v242
	v_mul_f32_e32 v223, v223, v242
	v_cvt_scalef32_pk_fp4_f32 v252, v208, v209, 1.0
	v_cvt_scalef32_pk_fp4_f32 v253, v216, v217, 1.0
	v_cvt_scalef32_pk_fp4_f32 v252, v210, v211, 1.0 op_sel:[0,0,1,0]
	v_cvt_scalef32_pk_fp4_f32 v253, v218, v219, 1.0 op_sel:[0,0,1,0]
	v_cvt_scalef32_pk_fp4_f32 v252, v212, v213, 1.0 op_sel:[0,0,0,1]
	v_cvt_scalef32_pk_fp4_f32 v253, v220, v221, 1.0 op_sel:[0,0,0,1]
	v_cvt_scalef32_pk_fp4_f32 v252, v214, v215, 1.0 op_sel:[0,0,1,1]
	v_cvt_scalef32_pk_fp4_f32 v253, v222, v223, 1.0 op_sel:[0,0,1,1]
	v_readlane_b32 s88, v244, 28
	v_readlane_b32 s89, v244, 29
	s_lshl_b32 s96, s84, 9
	s_nop 1
	s_add_u32 s88, s88, 0x4280000
	s_addc_u32 s89, s89, 0
	s_add_u32 s88, s88, s96
	s_addc_u32 s89, s89, 0
	s_nop 0
	global_store_dwordx2 v255, v[252:253], s[88:89]
	v_readlane_b32 s88, v244, 28
	v_readlane_b32 s89, v244, 29
	s_lshl_b32 s96, s84, 2
	s_nop 1
	s_add_u32 s88, s88, 0xa310800
	s_addc_u32 s89, s89, 0
	s_add_u32 s88, s88, s96
	s_addc_u32 s89, s89, 0
	s_mov_b64 exec, 1
	global_store_dword v251, v250, s[88:89]
	s_mov_b64 exec, -1
	s_add_u32 s86, s86, s85
	s_min_u32 s87, s86, s90
	s_and_b32 s96, s87, 0x4000
	s_cmp_eq_u32 s96, 0
	s_cselect_b32 s94, s98, s100
	s_cselect_b32 s95, s99, s101
	s_and_b32 s96, s87, 0x3fff
	s_lshl_b32 s96, s96, 12
	s_add_u32 s94, s94, s96
	s_addc_u32 s95, s95, 0
	s_lshr_b32 s96, s87, 15
	s_lshl_b32 s96, s96, 26
	s_add_u32 s94, s94, s96
	s_addc_u32 s95, s95, 0
	global_load_dwordx4 v[192:195], v254, s[94:95] nt
	global_load_dwordx4 v[196:199], v254, s[94:95] offset:16 nt
	global_load_dwordx4 v[200:203], v254, s[94:95] offset:32 nt
	global_load_dwordx4 v[204:207], v254, s[94:95] offset:48 nt
	s_add_u32 s84, s84, s85
	s_cmp_ge_u32 s84, 0xba98
	s_cbranch_scc1 .Ltc_p8_done
	s_waitcnt vmcnt(12)
	v_max_f32_e64 v240, |v224|, |v225|
	v_max3_f32 v240, |v226|, |v227|, v240
	v_max3_f32 v240, |v228|, |v229|, v240
	v_max3_f32 v240, |v230|, |v231|, v240
	v_max3_f32 v240, |v232|, |v233|, v240
	v_max3_f32 v240, |v234|, |v235|, v240
	v_max3_f32 v240, |v236|, |v237|, v240
	v_max3_f32 v240, |v238|, |v239|, v240
	s_nop 1
	v_mov_b32_dpp v241, v240 quad_perm:[1,0,3,2] row_mask:0xf bank_mask:0xf bound_ctrl:1
	v_max_f32_e32 v241, v241, v241
	v_max_f32_e32 v240, v240, v241
	s_nop 1
	v_mov_b32_dpp v241, v240 quad_perm:[2,3,0,1] row_mask:0xf bank_mask:0xf bound_ctrl:1
	v_max_f32_e32 v241, v241, v241
	v_max_f32_e32 v240, v240, v241
	s_nop 1
	v_mov_b32_dpp v241, v240 row_half_mirror row_mask:0xf bank_mask:0xf bound_ctrl:1
	v_max_f32_e32 v241, v241, v241
	v_max_f32_e32 v240, v240, v241
	s_nop 1
	v_mov_b32_dpp v241, v240 row_mirror row_mask:0xf bank_mask:0xf bound_ctrl:1
	v_max_f32_e32 v241, v241, v241
	v_max_f32_e32 v240, v240, v241
	s_nop 0
	v_readlane_b32 s96, v240, 32
	v_readlane_b32 s97, v240, 48
	v_readlane_b32 s92, v240, 0
	v_readlane_b32 s93, v240, 16
	s_nop 1
	v_max_f32_e64 v240, s97, s97
	v_max_f32_e64 v241, s96, s96
	v_mov_b32_e32 v248, s93
	v_max_f32_e32 v240, v241, v240
	v_max3_f32 v240, s92, v248, v240
	v_div_scale_f32 v243, s[92:93], v240, v240, s91
	v_rcp_f32_e32 v246, v243
	v_div_scale_f32 v247, vcc, s91, v240, s91
	v_fma_f32 v248, -v243, v246, 1.0
	v_fmac_f32_e32 v246, v248, v246
	v_mul_f32_e32 v249, v247, v246
	v_fma_f32 v248, -v243, v249, v247
	v_fmac_f32_e32 v249, v248, v246
	v_fma_f32 v248, -v243, v249, v247
	v_div_fmas_f32 v242, v248, v246, v249
	v_div_fixup_f32 v242, v242, v240, s91
	v_cmp_lt_f32_e32 vcc, 0, v240
	v_mov_b32_e32 v252, 0
	v_mov_b32_e32 v253, 0
	v_cndmask_b32_e32 v242, 0, v242, vcc
	v_mul_f32_e32 v250, 0x3e2aaaab, v240
	v_mul_f32_e32 v224, v224, v242
	v_mul_f32_e32 v225, v225, v242
	v_mul_f32_e32 v226, v226, v242
	v_mul_f32_e32 v227, v227, v242
	v_mul_f32_e32 v228, v228, v242
	v_mul_f32_e32 v229, v229, v242
	v_mul_f32_e32 v230, v230, v242
	v_mul_f32_e32 v231, v231, v242
	v_mul_f32_e32 v232, v232, v242
	v_mul_f32_e32 v233, v233, v242
	v_mul_f32_e32 v234, v234, v242
	v_mul_f32_e32 v235, v235, v242
	v_mul_f32_e32 v236, v236, v242
	v_mul_f32_e32 v237, v237, v242
	v_mul_f32_e32 v238, v238, v242
	v_mul_f32_e32 v239, v239, v242
	v_cvt_scalef32_pk_fp4_f32 v252, v224, v225, 1.0
	v_cvt_scalef32_pk_fp4_f32 v253, v232, v233, 1.0
	v_cvt_scalef32_pk_fp4_f32 v252, v226, v227, 1.0 op_sel:[0,0,1,0]
	v_cvt_scalef32_pk_fp4_f32 v253, v234, v235, 1.0 op_sel:[0,0,1,0]
	v_cvt_scalef32_pk_fp4_f32 v252, v228, v229, 1.0 op_sel:[0,0,0,1]
	v_cvt_scalef32_pk_fp4_f32 v253, v236, v237, 1.0 op_sel:[0,0,0,1]
	v_cvt_scalef32_pk_fp4_f32 v252, v230, v231, 1.0 op_sel:[0,0,1,1]
	v_cvt_scalef32_pk_fp4_f32 v253, v238, v239, 1.0 op_sel:[0,0,1,1]
	v_readlane_b32 s88, v244, 28
	v_readlane_b32 s89, v244, 29
	s_lshl_b32 s96, s84, 9
	s_nop 1
	s_add_u32 s88, s88, 0x4280000
	s_addc_u32 s89, s89, 0
	s_add_u32 s88, s88, s96
	s_addc_u32 s89, s89, 0
	s_nop 0
	global_store_dwordx2 v255, v[252:253], s[88:89]
	v_readlane_b32 s88, v244, 28
	v_readlane_b32 s89, v244, 29
	s_lshl_b32 s96, s84, 2
	s_nop 1
	s_add_u32 s88, s88, 0xa310800
	s_addc_u32 s89, s89, 0
	s_add_u32 s88, s88, s96
	s_addc_u32 s89, s89, 0
	s_mov_b64 exec, 1
	global_store_dword v251, v250, s[88:89]
	s_mov_b64 exec, -1
	s_add_u32 s86, s86, s85
	s_min_u32 s87, s86, s90
	s_and_b32 s96, s87, 0x4000
	s_cmp_eq_u32 s96, 0
	s_cselect_b32 s94, s98, s100
	s_cselect_b32 s95, s99, s101
	s_and_b32 s96, s87, 0x3fff
	s_lshl_b32 s96, s96, 12
	s_add_u32 s94, s94, s96
	s_addc_u32 s95, s95, 0
	s_lshr_b32 s96, s87, 15
	s_lshl_b32 s96, s96, 26
	s_add_u32 s94, s94, s96
	s_addc_u32 s95, s95, 0
	global_load_dwordx4 v[208:211], v254, s[94:95] nt
	global_load_dwordx4 v[212:215], v254, s[94:95] offset:16 nt
	global_load_dwordx4 v[216:219], v254, s[94:95] offset:32 nt
	global_load_dwordx4 v[220:223], v254, s[94:95] offset:48 nt
	s_add_u32 s84, s84, s85
	s_branch .Ltc_p8_loop

.Ltc_p8_end:
.LBB0_1953:
	v_readlane_b32 s4, v245, 7
	v_readlane_b32 s5, v245, 8
	s_cmp_gt_i32 s4, 9
	s_cselect_b64 s[0:1], -1, 0
	s_cmp_lt_i32 s5, 10
	s_cselect_b64 s[2:3], -1, 0
	s_or_b64 s[2:3], s[0:1], s[2:3]
	s_and_b64 vcc, exec, s[2:3]
	v_readlane_b32 s6, v245, 9
	v_readlane_b32 s7, v245, 10
	s_cbranch_vccnz .LBB0_2023
	s_andn2_b64 vcc, exec, s[20:21]
	s_cbranch_vccnz .LBB0_1956
	v_and_b32_e32 v4, 0x3ff, v0
	s_cbranch_execz .LBB0_1957
	s_branch .LBB0_2019

.Ltc_p15:
	s_mov_b64 exec, -1
	v_readlane_b32 s84, v245, 0
	s_nop 3
	s_and_b32 s97, s84, 0xff
	s_cmp_lt_u32 s97, 40
	s_cbranch_scc1 .Ltc_p15_end
	v_and_b32_e32 v255, 63, v0
	v_lshlrev_b32_e32 v254, 6, v255
	v_lshlrev_b32_e32 v255, 3, v255
	v_mov_b32_e32 v251, 0
	v_readfirstlane_b32 s96, v0
	v_readlane_b32 s98, v244, 22
	v_readlane_b32 s99, v244, 23
	v_readlane_b32 s100, v244, 24
	v_readlane_b32 s101, v244, 25
	s_nop 3
	s_and_b32 s96, s96, 0x3ff
	s_lshr_b32 s96, s96, 6
	s_sub_u32 s97, s97, 40
	s_lshr_b32 s84, s84, 8
	s_mul_i32 s84, s84, 216
	s_add_u32 s84, s84, s97
	s_lshl_b32 s84, s84, 2
	s_add_u32 s84, s84, s96
	s_add_u32 s84, s84, 0xba98
	s_mov_b32 s85, 1728
	s_mov_b32 s91, 0x40c00000
	s_cmp_ge_u32 s84, 0xdcd8
	s_cbranch_scc1 .Ltc_p15_end
	s_mov_b32 s90, s84
.Ltc_p15_last:
	s_add_u32 s87, s90, s85
	s_cmp_ge_u32 s87, 0xdcd8
	s_cbranch_scc1 .Ltc_p15_lastd
	s_mov_b32 s90, s87
	s_branch .Ltc_p15_last

.Ltc_p15_loop:
	s_cmp_ge_u32 s84, 0xdcd8
	s_cbranch_scc1 .Ltc_p15_done
	s_waitcnt vmcnt(12)
	v_max_f32_e64 v240, |v176|, |v177|
	v_max3_f32 v240, |v178|, |v179|, v240
	v_max3_f32 v240, |v180|, |v181|, v240
	v_max3_f32 v240, |v182|, |v183|, v240
	v_max3_f32 v240, |v184|, |v185|, v240
	v_max3_f32 v240, |v186|, |v187|, v240
	v_max3_f32 v240, |v188|, |v189|, v240
	v_max3_f32 v240, |v190|, |v191|, v240
	s_nop 1
	v_mov_b32_dpp v241, v240 quad_perm:[1,0,3,2] row_mask:0xf bank_mask:0xf bound_ctrl:1
	v_max_f32_e32 v241, v241, v241
	v_max_f32_e32 v240, v240, v241
	s_nop 1
	v_mov_b32_dpp v241, v240 quad_perm:[2,3,0,1] row_mask:0xf bank_mask:0xf bound_ctrl:1
	v_max_f32_e32 v241, v241, v241
	v_max_f32_e32 v240, v240, v241
	s_nop 1
	v_mov_b32_dpp v241, v240 row_half_mirror row_mask:0xf bank_mask:0xf bound_ctrl:1
	v_max_f32_e32 v241, v241, v241
	v_max_f32_e32 v240, v240, v241
	s_nop 1
	v_mov_b32_dpp v241, v240 row_mirror row_mask:0xf bank_mask:0xf bound_ctrl:1
	v_max_f32_e32 v241, v241, v241
	v_max_f32_e32 v240, v240, v241
	s_nop 0
	v_readlane_b32 s96, v240, 32
	v_readlane_b32 s97, v240, 48
	v_readlane_b32 s92, v240, 0
	v_readlane_b32 s93, v240, 16
	s_nop 1
	v_max_f32_e64 v240, s97, s97
	v_max_f32_e64 v241, s96, s96
	v_mov_b32_e32 v248, s93
	v_max_f32_e32 v240, v241, v240
	v_max3_f32 v240, s92, v248, v240
	v_div_scale_f32 v243, s[92:93], v240, v240, s91
	v_rcp_f32_e32 v246, v243
	v_div_scale_f32 v247, vcc, s91, v240, s91
	v_fma_f32 v248, -v243, v246, 1.0
	v_fmac_f32_e32 v246, v248, v246
	v_mul_f32_e32 v249, v247, v246
	v_fma_f32 v248, -v243, v249, v247
	v_fmac_f32_e32 v249, v248, v246
	v_fma_f32 v248, -v243, v249, v247
	v_div_fmas_f32 v242, v248, v246, v249
	v_div_fixup_f32 v242, v242, v240, s91
	v_cmp_lt_f32_e32 vcc, 0, v240
	v_mov_b32_e32 v252, 0
	v_mov_b32_e32 v253, 0
	v_cndmask_b32_e32 v242, 0, v242, vcc
	v_mul_f32_e32 v250, 0x3e2aaaab, v240
	v_mul_f32_e32 v176, v176, v242
	v_mul_f32_e32 v177, v177, v242
	v_mul_f32_e32 v178, v178, v242
	v_mul_f32_e32 v179, v179, v242
	v_mul_f32_e32 v180, v180, v242
	v_mul_f32_e32 v181, v181, v242
	v_mul_f32_e32 v182, v182, v242
	v_mul_f32_e32 v183, v183, v242
	v_mul_f32_e32 v184, v184, v242
	v_mul_f32_e32 v185, v185, v242
	v_mul_f32_e32 v186, v186, v242
	v_mul_f32_e32 v187, v187, v242
	v_mul_f32_e32 v188, v188, v242
	v_mul_f32_e32 v189, v189, v242
	v_mul_f32_e32 v190, v190, v242
	v_mul_f32_e32 v191, v191, v242
	v_cvt_scalef32_pk_fp4_f32 v252, v176, v177, 1.0
	v_cvt_scalef32_pk_fp4_f32 v253, v184, v185, 1.0
	v_cvt_scalef32_pk_fp4_f32 v252, v178, v179, 1.0 op_sel:[0,0,1,0]
	v_cvt_scalef32_pk_fp4_f32 v253, v186, v187, 1.0 op_sel:[0,0,1,0]
	v_cvt_scalef32_pk_fp4_f32 v252, v180, v181, 1.0 op_sel:[0,0,0,1]
	v_cvt_scalef32_pk_fp4_f32 v253, v188, v189, 1.0 op_sel:[0,0,0,1]
	v_cvt_scalef32_pk_fp4_f32 v252, v182, v183, 1.0 op_sel:[0,0,1,1]
	v_cvt_scalef32_pk_fp4_f32 v253, v190, v191, 1.0 op_sel:[0,0,1,1]
	v_readlane_b32 s88, v244, 28
	v_readlane_b32 s89, v244, 29
	s_lshl_b32 s96, s84, 9
	s_nop 1
	s_add_u32 s88, s88, 0x4280000
	s_addc_u32 s89, s89, 0
	s_add_u32 s88, s88, s96
	s_addc_u32 s89, s89, 0
	s_nop 0
	global_store_dwordx2 v255, v[252:253], s[88:89]
	v_readlane_b32 s88, v244, 28
	v_readlane_b32 s89, v244, 29
	s_lshl_b32 s96, s84, 2
	s_nop 1
	s_add_u32 s88, s88, 0xa310800
	s_addc_u32 s89, s89, 0
	s_add_u32 s88, s88, s96
	s_addc_u32 s89, s89, 0
	s_mov_b64 exec, 1
	global_store_dword v251, v250, s[88:89]
	s_mov_b64 exec, -1
	s_add_u32 s86, s86, s85
	s_min_u32 s87, s86, s90
	s_and_b32 s96, s87, 0x4000
	s_cmp_eq_u32 s96, 0
	s_cselect_b32 s94, s98, s100
	s_cselect_b32 s95, s99, s101
	s_and_b32 s96, s87, 0x3fff
	s_lshl_b32 s96, s96, 12
	s_add_u32 s94, s94, s96
	s_addc_u32 s95, s95, 0
	s_lshr_b32 s96, s87, 15
	s_lshl_b32 s96, s96, 26
	s_add_u32 s94, s94, s96
	s_addc_u32 s95, s95, 0
	global_load_dwordx4 v[224:227], v254, s[94:95] nt
	global_load_dwordx4 v[228:231], v254, s[94:95] offset:16 nt
	global_load_dwordx4 v[232:235], v254, s[94:95] offset:32 nt
	global_load_dwordx4 v[236:239], v254, s[94:95] offset:48 nt
	s_add_u32 s84, s84, s85
	s_cmp_ge_u32 s84, 0xdcd8
	s_cbranch_scc1 .Ltc_p15_done
	s_waitcnt vmcnt(12)
	v_max_f32_e64 v240, |v192|, |v193|
	v_max3_f32 v240, |v194|, |v195|, v240
	v_max3_f32 v240, |v196|, |v197|, v240
	v_max3_f32 v240, |v198|, |v199|, v240
	v_max3_f32 v240, |v200|, |v201|, v240
	v_max3_f32 v240, |v202|, |v203|, v240
	v_max3_f32 v240, |v204|, |v205|, v240
	v_max3_f32 v240, |v206|, |v207|, v240
	s_nop 1
	v_mov_b32_dpp v241, v240 quad_perm:[1,0,3,2] row_mask:0xf bank_mask:0xf bound_ctrl:1
	v_max_f32_e32 v241, v241, v241
	v_max_f32_e32 v240, v240, v241
	s_nop 1
	v_mov_b32_dpp v241, v240 quad_perm:[2,3,0,1] row_mask:0xf bank_mask:0xf bound_ctrl:1
	v_max_f32_e32 v241, v241, v241
	v_max_f32_e32 v240, v240, v241
	s_nop 1
	v_mov_b32_dpp v241, v240 row_half_mirror row_mask:0xf bank_mask:0xf bound_ctrl:1
	v_max_f32_e32 v241, v241, v241
	v_max_f32_e32 v240, v240, v241
	s_nop 1
	v_mov_b32_dpp v241, v240 row_mirror row_mask:0xf bank_mask:0xf bound_ctrl:1
	v_max_f32_e32 v241, v241, v241
	v_max_f32_e32 v240, v240, v241
	s_nop 0
	v_readlane_b32 s96, v240, 32
	v_readlane_b32 s97, v240, 48
	v_readlane_b32 s92, v240, 0
	v_readlane_b32 s93, v240, 16
	s_nop 1
	v_max_f32_e64 v240, s97, s97
	v_max_f32_e64 v241, s96, s96
	v_mov_b32_e32 v248, s93
	v_max_f32_e32 v240, v241, v240
	v_max3_f32 v240, s92, v248, v240
	v_div_scale_f32 v243, s[92:93], v240, v240, s91
	v_rcp_f32_e32 v246, v243
	v_div_scale_f32 v247, vcc, s91, v240, s91
	v_fma_f32 v248, -v243, v246, 1.0
	v_fmac_f32_e32 v246, v248, v246
	v_mul_f32_e32 v249, v247, v246
	v_fma_f32 v248, -v243, v249, v247
	v_fmac_f32_e32 v249, v248, v246
	v_fma_f32 v248, -v243, v249, v247
	v_div_fmas_f32 v242, v248, v246, v249
	v_div_fixup_f32 v242, v242, v240, s91
	v_cmp_lt_f32_e32 vcc, 0, v240
	v_mov_b32_e32 v252, 0
	v_mov_b32_e32 v253, 0
	v_cndmask_b32_e32 v242, 0, v242, vcc
	v_mul_f32_e32 v250, 0x3e2aaaab, v240
	v_mul_f32_e32 v192, v192, v242
	v_mul_f32_e32 v193, v193, v242
	v_mul_f32_e32 v194, v194, v242
	v_mul_f32_e32 v195, v195, v242
	v_mul_f32_e32 v196, v196, v242
	v_mul_f32_e32 v197, v197, v242
	v_mul_f32_e32 v198, v198, v242
	v_mul_f32_e32 v199, v199, v242
	v_mul_f32_e32 v200, v200, v242
	v_mul_f32_e32 v201, v201, v242
	v_mul_f32_e32 v202, v202, v242
	v_mul_f32_e32 v203, v203, v242
	v_mul_f32_e32 v204, v204, v242
	v_mul_f32_e32 v205, v205, v242
	v_mul_f32_e32 v206, v206, v242
	v_mul_f32_e32 v207, v207, v242
	v_cvt_scalef32_pk_fp4_f32 v252, v192, v193, 1.0
	v_cvt_scalef32_pk_fp4_f32 v253, v200, v201, 1.0
	v_cvt_scalef32_pk_fp4_f32 v252, v194, v195, 1.0 op_sel:[0,0,1,0]
	v_cvt_scalef32_pk_fp4_f32 v253, v202, v203, 1.0 op_sel:[0,0,1,0]
	v_cvt_scalef32_pk_fp4_f32 v252, v196, v197, 1.0 op_sel:[0,0,0,1]
	v_cvt_scalef32_pk_fp4_f32 v253, v204, v205, 1.0 op_sel:[0,0,0,1]
	v_cvt_scalef32_pk_fp4_f32 v252, v198, v199, 1.0 op_sel:[0,0,1,1]
	v_cvt_scalef32_pk_fp4_f32 v253, v206, v207, 1.0 op_sel:[0,0,1,1]
	v_readlane_b32 s88, v244, 28
	v_readlane_b32 s89, v244, 29
	s_lshl_b32 s96, s84, 9
	s_nop 1
	s_add_u32 s88, s88, 0x4280000
	s_addc_u32 s89, s89, 0
	s_add_u32 s88, s88, s96
	s_addc_u32 s89, s89, 0
	s_nop 0
	global_store_dwordx2 v255, v[252:253], s[88:89]
	v_readlane_b32 s88, v244, 28
	v_readlane_b32 s89, v244, 29
	s_lshl_b32 s96, s84, 2
	s_nop 1
	s_add_u32 s88, s88, 0xa310800
	s_addc_u32 s89, s89, 0
	s_add_u32 s88, s88, s96
	s_addc_u32 s89, s89, 0
	s_mov_b64 exec, 1
	global_store_dword v251, v250, s[88:89]
	s_mov_b64 exec, -1
	s_add_u32 s86, s86, s85
	s_min_u32 s87, s86, s90
	s_and_b32 s96, s87, 0x4000
	s_cmp_eq_u32 s96, 0
	s_cselect_b32 s94, s98, s100
	s_cselect_b32 s95, s99, s101
	s_and_b32 s96, s87, 0x3fff
	s_lshl_b32 s96, s96, 12
	s_add_u32 s94, s94, s96
	s_addc_u32 s95, s95, 0
	s_lshr_b32 s96, s87, 15
	s_lshl_b32 s96, s96, 26
	s_add_u32 s94, s94, s96
	s_addc_u32 s95, s95, 0
	global_load_dwordx4 v[176:179], v254, s[94:95] nt
	global_load_dwordx4 v[180:183], v254, s[94:95] offset:16 nt
	global_load_dwordx4 v[184:187], v254, s[94:95] offset:32 nt
	global_load_dwordx4 v[188:191], v254, s[94:95] offset:48 nt
	s_add_u32 s84, s84, s85
	s_cmp_ge_u32 s84, 0xdcd8
	s_cbranch_scc1 .Ltc_p15_done
	s_waitcnt vmcnt(12)
	v_max_f32_e64 v240, |v208|, |v209|
	v_max3_f32 v240, |v210|, |v211|, v240
	v_max3_f32 v240, |v212|, |v213|, v240
	v_max3_f32 v240, |v214|, |v215|, v240
	v_max3_f32 v240, |v216|, |v217|, v240
	v_max3_f32 v240, |v218|, |v219|, v240
	v_max3_f32 v240, |v220|, |v221|, v240
	v_max3_f32 v240, |v222|, |v223|, v240
	s_nop 1
	v_mov_b32_dpp v241, v240 quad_perm:[1,0,3,2] row_mask:0xf bank_mask:0xf bound_ctrl:1
	v_max_f32_e32 v241, v241, v241
	v_max_f32_e32 v240, v240, v241
	s_nop 1
	v_mov_b32_dpp v241, v240 quad_perm:[2,3,0,1] row_mask:0xf bank_mask:0xf bound_ctrl:1
	v_max_f32_e32 v241, v241, v241
	v_max_f32_e32 v240, v240, v241
	s_nop 1
	v_mov_b32_dpp v241, v240 row_half_mirror row_mask:0xf bank_mask:0xf bound_ctrl:1
	v_max_f32_e32 v241, v241, v241
	v_max_f32_e32 v240, v240, v241
	s_nop 1
	v_mov_b32_dpp v241, v240 row_mirror row_mask:0xf bank_mask:0xf bound_ctrl:1
	v_max_f32_e32 v241, v241, v241
	v_max_f32_e32 v240, v240, v241
	s_nop 0
	v_readlane_b32 s96, v240, 32
	v_readlane_b32 s97, v240, 48
	v_readlane_b32 s92, v240, 0
	v_readlane_b32 s93, v240, 16
	s_nop 1
	v_max_f32_e64 v240, s97, s97
	v_max_f32_e64 v241, s96, s96
	v_mov_b32_e32 v248, s93
	v_max_f32_e32 v240, v241, v240
	v_max3_f32 v240, s92, v248, v240
	v_div_scale_f32 v243, s[92:93], v240, v240, s91
	v_rcp_f32_e32 v246, v243
	v_div_scale_f32 v247, vcc, s91, v240, s91
	v_fma_f32 v248, -v243, v246, 1.0
	v_fmac_f32_e32 v246, v248, v246
	v_mul_f32_e32 v249, v247, v246
	v_fma_f32 v248, -v243, v249, v247
	v_fmac_f32_e32 v249, v248, v246
	v_fma_f32 v248, -v243, v249, v247
	v_div_fmas_f32 v242, v248, v246, v249
	v_div_fixup_f32 v242, v242, v240, s91
	v_cmp_lt_f32_e32 vcc, 0, v240
	v_mov_b32_e32 v252, 0
	v_mov_b32_e32 v253, 0
	v_cndmask_b32_e32 v242, 0, v242, vcc
	v_mul_f32_e32 v250, 0x3e2aaaab, v240
	v_mul_f32_e32 v208, v208, v242
	v_mul_f32_e32 v209, v209, v242
	v_mul_f32_e32 v210, v210, v242
	v_mul_f32_e32 v211, v211, v242
	v_mul_f32_e32 v212, v212, v242
	v_mul_f32_e32 v213, v213, v242
	v_mul_f32_e32 v214, v214, v242
	v_mul_f32_e32 v215, v215, v242
	v_mul_f32_e32 v216, v216, v242
	v_mul_f32_e32 v217, v217, v242
	v_mul_f32_e32 v218, v218, v242
	v_mul_f32_e32 v219, v219, v242
	v_mul_f32_e32 v220, v220, v242
	v_mul_f32_e32 v221, v221, v242
	v_mul_f32_e32 v222, v222, v242
	v_mul_f32_e32 v223, v223, v242
	v_cvt_scalef32_pk_fp4_f32 v252, v208, v209, 1.0
	v_cvt_scalef32_pk_fp4_f32 v253, v216, v217, 1.0
	v_cvt_scalef32_pk_fp4_f32 v252, v210, v211, 1.0 op_sel:[0,0,1,0]
	v_cvt_scalef32_pk_fp4_f32 v253, v218, v219, 1.0 op_sel:[0,0,1,0]
	v_cvt_scalef32_pk_fp4_f32 v252, v212, v213, 1.0 op_sel:[0,0,0,1]
	v_cvt_scalef32_pk_fp4_f32 v253, v220, v221, 1.0 op_sel:[0,0,0,1]
	v_cvt_scalef32_pk_fp4_f32 v252, v214, v215, 1.0 op_sel:[0,0,1,1]
	v_cvt_scalef32_pk_fp4_f32 v253, v222, v223, 1.0 op_sel:[0,0,1,1]
	v_readlane_b32 s88, v244, 28
	v_readlane_b32 s89, v244, 29
	s_lshl_b32 s96, s84, 9
	s_nop 1
	s_add_u32 s88, s88, 0x4280000
	s_addc_u32 s89, s89, 0
	s_add_u32 s88, s88, s96
	s_addc_u32 s89, s89, 0
	s_nop 0
	global_store_dwordx2 v255, v[252:253], s[88:89]
	v_readlane_b32 s88, v244, 28
	v_readlane_b32 s89, v244, 29
	s_lshl_b32 s96, s84, 2
	s_nop 1
	s_add_u32 s88, s88, 0xa310800
	s_addc_u32 s89, s89, 0
	s_add_u32 s88, s88, s96
	s_addc_u32 s89, s89, 0
	s_mov_b64 exec, 1
	global_store_dword v251, v250, s[88:89]
	s_mov_b64 exec, -1
	s_add_u32 s86, s86, s85
	s_min_u32 s87, s86, s90
	s_and_b32 s96, s87, 0x4000
	s_cmp_eq_u32 s96, 0
	s_cselect_b32 s94, s98, s100
	s_cselect_b32 s95, s99, s101
	s_and_b32 s96, s87, 0x3fff
	s_lshl_b32 s96, s96, 12
	s_add_u32 s94, s94, s96
	s_addc_u32 s95, s95, 0
	s_lshr_b32 s96, s87, 15
	s_lshl_b32 s96, s96, 26
	s_add_u32 s94, s94, s96
	s_addc_u32 s95, s95, 0
	global_load_dwordx4 v[192:195], v254, s[94:95] nt
	global_load_dwordx4 v[196:199], v254, s[94:95] offset:16 nt
	global_load_dwordx4 v[200:203], v254, s[94:95] offset:32 nt
	global_load_dwordx4 v[204:207], v254, s[94:95] offset:48 nt
	s_add_u32 s84, s84, s85
	s_cmp_ge_u32 s84, 0xdcd8
	s_cbranch_scc1 .Ltc_p15_done
	s_waitcnt vmcnt(12)
	v_max_f32_e64 v240, |v224|, |v225|
	v_max3_f32 v240, |v226|, |v227|, v240
	v_max3_f32 v240, |v228|, |v229|, v240
	v_max3_f32 v240, |v230|, |v231|, v240
	v_max3_f32 v240, |v232|, |v233|, v240
	v_max3_f32 v240, |v234|, |v235|, v240
	v_max3_f32 v240, |v236|, |v237|, v240
	v_max3_f32 v240, |v238|, |v239|, v240
	s_nop 1
	v_mov_b32_dpp v241, v240 quad_perm:[1,0,3,2] row_mask:0xf bank_mask:0xf bound_ctrl:1
	v_max_f32_e32 v241, v241, v241
	v_max_f32_e32 v240, v240, v241
	s_nop 1
	v_mov_b32_dpp v241, v240 quad_perm:[2,3,0,1] row_mask:0xf bank_mask:0xf bound_ctrl:1
	v_max_f32_e32 v241, v241, v241
	v_max_f32_e32 v240, v240, v241
	s_nop 1
	v_mov_b32_dpp v241, v240 row_half_mirror row_mask:0xf bank_mask:0xf bound_ctrl:1
	v_max_f32_e32 v241, v241, v241
	v_max_f32_e32 v240, v240, v241
	s_nop 1
	v_mov_b32_dpp v241, v240 row_mirror row_mask:0xf bank_mask:0xf bound_ctrl:1
	v_max_f32_e32 v241, v241, v241
	v_max_f32_e32 v240, v240, v241
	s_nop 0
	v_readlane_b32 s96, v240, 32
	v_readlane_b32 s97, v240, 48
	v_readlane_b32 s92, v240, 0
	v_readlane_b32 s93, v240, 16
	s_nop 1
	v_max_f32_e64 v240, s97, s97
	v_max_f32_e64 v241, s96, s96
	v_mov_b32_e32 v248, s93
	v_max_f32_e32 v240, v241, v240
	v_max3_f32 v240, s92, v248, v240
	v_div_scale_f32 v243, s[92:93], v240, v240, s91
	v_rcp_f32_e32 v246, v243
	v_div_scale_f32 v247, vcc, s91, v240, s91
	v_fma_f32 v248, -v243, v246, 1.0
	v_fmac_f32_e32 v246, v248, v246
	v_mul_f32_e32 v249, v247, v246
	v_fma_f32 v248, -v243, v249, v247
	v_fmac_f32_e32 v249, v248, v246
	v_fma_f32 v248, -v243, v249, v247
	v_div_fmas_f32 v242, v248, v246, v249
	v_div_fixup_f32 v242, v242, v240, s91
	v_cmp_lt_f32_e32 vcc, 0, v240
	v_mov_b32_e32 v252, 0
	v_mov_b32_e32 v253, 0
	v_cndmask_b32_e32 v242, 0, v242, vcc
	v_mul_f32_e32 v250, 0x3e2aaaab, v240
	v_mul_f32_e32 v224, v224, v242
	v_mul_f32_e32 v225, v225, v242
	v_mul_f32_e32 v226, v226, v242
	v_mul_f32_e32 v227, v227, v242
	v_mul_f32_e32 v228, v228, v242
	v_mul_f32_e32 v229, v229, v242
	v_mul_f32_e32 v230, v230, v242
	v_mul_f32_e32 v231, v231, v242
	v_mul_f32_e32 v232, v232, v242
	v_mul_f32_e32 v233, v233, v242
	v_mul_f32_e32 v234, v234, v242
	v_mul_f32_e32 v235, v235, v242
	v_mul_f32_e32 v236, v236, v242
	v_mul_f32_e32 v237, v237, v242
	v_mul_f32_e32 v238, v238, v242
	v_mul_f32_e32 v239, v239, v242
	v_cvt_scalef32_pk_fp4_f32 v252, v224, v225, 1.0
	v_cvt_scalef32_pk_fp4_f32 v253, v232, v233, 1.0
	v_cvt_scalef32_pk_fp4_f32 v252, v226, v227, 1.0 op_sel:[0,0,1,0]
	v_cvt_scalef32_pk_fp4_f32 v253, v234, v235, 1.0 op_sel:[0,0,1,0]
	v_cvt_scalef32_pk_fp4_f32 v252, v228, v229, 1.0 op_sel:[0,0,0,1]
	v_cvt_scalef32_pk_fp4_f32 v253, v236, v237, 1.0 op_sel:[0,0,0,1]
	v_cvt_scalef32_pk_fp4_f32 v252, v230, v231, 1.0 op_sel:[0,0,1,1]
	v_cvt_scalef32_pk_fp4_f32 v253, v238, v239, 1.0 op_sel:[0,0,1,1]
	v_readlane_b32 s88, v244, 28
	v_readlane_b32 s89, v244, 29
	s_lshl_b32 s96, s84, 9
	s_nop 1
	s_add_u32 s88, s88, 0x4280000
	s_addc_u32 s89, s89, 0
	s_add_u32 s88, s88, s96
	s_addc_u32 s89, s89, 0
	s_nop 0
	global_store_dwordx2 v255, v[252:253], s[88:89]
	v_readlane_b32 s88, v244, 28
	v_readlane_b32 s89, v244, 29
	s_lshl_b32 s96, s84, 2
	s_nop 1
	s_add_u32 s88, s88, 0xa310800
	s_addc_u32 s89, s89, 0
	s_add_u32 s88, s88, s96
	s_addc_u32 s89, s89, 0
	s_mov_b64 exec, 1
	global_store_dword v251, v250, s[88:89]
	s_mov_b64 exec, -1
	s_add_u32 s86, s86, s85
	s_min_u32 s87, s86, s90
	s_and_b32 s96, s87, 0x4000
	s_cmp_eq_u32 s96, 0
	s_cselect_b32 s94, s98, s100
	s_cselect_b32 s95, s99, s101
	s_and_b32 s96, s87, 0x3fff
	s_lshl_b32 s96, s96, 12
	s_add_u32 s94, s94, s96
	s_addc_u32 s95, s95, 0
	s_lshr_b32 s96, s87, 15
	s_lshl_b32 s96, s96, 26
	s_add_u32 s94, s94, s96
	s_addc_u32 s95, s95, 0
	global_load_dwordx4 v[208:211], v254, s[94:95] nt
	global_load_dwordx4 v[212:215], v254, s[94:95] offset:16 nt
	global_load_dwordx4 v[216:219], v254, s[94:95] offset:32 nt
	global_load_dwordx4 v[220:223], v254, s[94:95] offset:48 nt
	s_add_u32 s84, s84, s85
	s_branch .Ltc_p15_loop

.Ltc_p17:
	s_mov_b64 exec, -1
	v_readlane_b32 s84, v245, 0
	s_nop 3
	s_and_b32 s97, s84, 0xff
	s_cmp_lt_u32 s97, 80
	s_cbranch_scc1 .Ltc_p17_end
	v_and_b32_e32 v255, 63, v0
	v_lshlrev_b32_e32 v254, 6, v255
	v_lshlrev_b32_e32 v255, 3, v255
	v_mov_b32_e32 v251, 0
	v_readfirstlane_b32 s96, v0
	v_readlane_b32 s98, v244, 22
	v_readlane_b32 s99, v244, 23
	v_readlane_b32 s100, v244, 24
	v_readlane_b32 s101, v244, 25
	s_nop 3
	s_and_b32 s96, s96, 0x3ff
	s_lshr_b32 s96, s96, 6
	s_sub_u32 s97, s97, 80
	s_lshr_b32 s84, s84, 8
	s_mul_i32 s84, s84, 176
	s_add_u32 s84, s84, s97
	s_lshl_b32 s84, s84, 2
	s_add_u32 s84, s84, s96
	s_add_u32 s84, s84, 0xdcd8
	s_mov_b32 s85, 1408
	s_mov_b32 s91, 0x40c00000
	s_cmp_ge_u32 s84, 0x10000
	s_cbranch_scc1 .Ltc_p17_end
	s_mov_b32 s90, s84
